# phase 1 row stream hand-written: 4 quarter-row loads per row in flight, two rows deep (hipcc waited vmcnt(0) after every 1 KB load)
# speedup vs baseline: 1.0391x; 1.0050x over previous
.LBB0_117:
	v_and_b32_e32 v2, 8, v5
	v_mul_u32_u24_e32 v2, 0x1800, v2
	v_and_or_b32 v2, v6, s6, v2
	v_lshlrev_b32_e32 v2, 2, v2
	global_load_dword v7, v2, s[0:1]
	v_lshl_add_u64 v[8:9], s[0:1], 0, v[2:3]
	v_add_co_u32_e32 v10, vcc, 0x6000, v8
	v_add_u32_e32 v12, 0x12000, v2
	s_nop 0
	v_addc_co_u32_e32 v11, vcc, 0, v9, vcc
	v_add_co_u32_e32 v8, vcc, 0xc000, v8
	v_add_u32_e32 v13, 0x18000, v2
	v_add_u32_e32 v14, 0x1e000, v2
	v_add_u32_e32 v15, 0x24000, v2
	v_add_u32_e32 v2, 0x2a000, v2
	v_addc_co_u32_e32 v9, vcc, 0, v9, vcc
	global_load_dword v10, v[10:11], off
	s_nop 0
	global_load_dword v8, v[8:9], off
	s_nop 0
	global_load_dword v9, v12, s[0:1]
	global_load_dword v11, v13, s[0:1]
	s_nop 0
	global_load_dword v12, v14, s[0:1]
	global_load_dword v13, v15, s[0:1]
	s_nop 0
	global_load_dword v2, v2, s[0:1]
	v_add_u32_e32 v14, 0x200, v6
	v_cmp_lt_u32_e32 vcc, s7, v6
	v_add_u32_e32 v5, 2, v5
	s_or_b64 s[4:5], vcc, s[4:5]
	v_mov_b32_e32 v6, v14
	s_waitcnt vmcnt(7)
	v_add_f32_e32 v7, 0, v7
	s_waitcnt vmcnt(6)
	v_add_f32_e32 v7, v7, v10
	s_waitcnt vmcnt(5)
	v_add_f32_e32 v7, v7, v8
	s_waitcnt vmcnt(4)
	v_add_f32_e32 v7, v7, v9
	s_waitcnt vmcnt(3)
	v_add_f32_e32 v7, v7, v11
	s_waitcnt vmcnt(2)
	v_add_f32_e32 v7, v7, v12
	s_waitcnt vmcnt(1)
	v_add_f32_e32 v7, v7, v13
	s_waitcnt vmcnt(0)
	v_add_f32_e32 v2, v7, v2
	ds_write_b32 v4, v2
	v_add_u32_e32 v4, 0x800, v4
	s_andn2_b64 exec, exec, s[4:5]
	s_cbranch_execnz .LBB0_117
	s_or_b64 exec, exec, s[4:5]
	v_lshrrev_b32_e32 v2, 6, v188
	v_lshl_add_u32 v6, s33, 3, v2
	s_movk_i32 s10, 0x4100
	v_cmp_gt_i32_e32 vcc, s10, v6
	s_waitcnt lgkmcnt(0)
	s_barrier
	s_and_saveexec_b64 s[0:1], vcc
	s_cbranch_execz .LBB0_131
	v_and_b32_e32 v1, 63, v188
	v_lshlrev_b32_e32 v2, 4, v1
	v_lshlrev_b32_e32 v3, 3, v1
	v_readfirstlane_b32 s8, v188
	s_lshr_b32 s8, s8, 6
	s_lshl_b32 s9, s33, 3
	s_add_i32 s9, s9, s8
	s_lshl_b32 s10, s9, 12
	s_add_u32 s4, s52, s10
	s_addc_u32 s5, s53, 0
	s_lshl_b32 s11, s9, 11
	s_add_u32 s6, s54, s11
	s_addc_u32 s7, s55, 0
	global_load_dwordx4 v[40:43], v2, s[4:5]
	global_load_dwordx4 v[44:47], v2, s[4:5] offset:1024
	global_load_dwordx4 v[48:51], v2, s[4:5] offset:2048
	global_load_dwordx4 v[52:55], v2, s[4:5] offset:3072
	s_add_u32 s4, s4, 0x800000
	s_addc_u32 s5, s5, 0
	global_load_dwordx4 v[56:59], v2, s[4:5]
	global_load_dwordx4 v[60:63], v2, s[4:5] offset:1024
	global_load_dwordx4 v[64:67], v2, s[4:5] offset:2048
	global_load_dwordx4 v[68:71], v2, s[4:5] offset:3072
	s_add_u32 s4, s4, 0x800000
	s_addc_u32 s5, s5, 0
	ds_read_b128 v[8:11], v2 offset:0
	ds_read_b128 v[12:15], v2 offset:1024
	ds_read_b128 v[16:19], v2 offset:2048
	ds_read_b128 v[20:23], v2 offset:3072
	ds_read_b128 v[24:27], v2 offset:4096
	ds_read_b128 v[28:31], v2 offset:5120
	ds_read_b128 v[32:35], v2 offset:6144
	ds_read_b128 v[36:39], v2 offset:7168
	s_waitcnt lgkmcnt(0)
	v_pk_add_f32 v[24:25], v[24:25], 1.0 op_sel_hi:[1,0]
	v_pk_add_f32 v[26:27], v[26:27], 1.0 op_sel_hi:[1,0]
	v_pk_add_f32 v[28:29], v[28:29], 1.0 op_sel_hi:[1,0]
	v_pk_add_f32 v[30:31], v[30:31], 1.0 op_sel_hi:[1,0]
	v_pk_add_f32 v[32:33], v[32:33], 1.0 op_sel_hi:[1,0]
	v_pk_add_f32 v[34:35], v[34:35], 1.0 op_sel_hi:[1,0]
	v_pk_add_f32 v[36:37], v[36:37], 1.0 op_sel_hi:[1,0]
	v_pk_add_f32 v[38:39], v[38:39], 1.0 op_sel_hi:[1,0]
	s_waitcnt vmcnt(4)
	v_pk_fma_f32 v[40:41], v[40:41], v[24:25], v[8:9]
	v_pk_fma_f32 v[42:43], v[42:43], v[26:27], v[10:11]
	v_pk_fma_f32 v[44:45], v[44:45], v[28:29], v[12:13]
	v_pk_fma_f32 v[46:47], v[46:47], v[30:31], v[14:15]
	v_pk_fma_f32 v[48:49], v[48:49], v[32:33], v[16:17]
	v_pk_fma_f32 v[50:51], v[50:51], v[34:35], v[18:19]
	v_pk_fma_f32 v[52:53], v[52:53], v[36:37], v[20:21]
	v_pk_fma_f32 v[54:55], v[54:55], v[38:39], v[22:23]
	v_cvt_pk_bf16_f32 v72, v40, v41
	v_cvt_pk_bf16_f32 v73, v42, v43
	v_cvt_pk_bf16_f32 v74, v44, v45
	v_cvt_pk_bf16_f32 v75, v46, v47
	v_cvt_pk_bf16_f32 v76, v48, v49
	v_cvt_pk_bf16_f32 v77, v50, v51
	v_cvt_pk_bf16_f32 v78, v52, v53
	v_cvt_pk_bf16_f32 v79, v54, v55
	global_store_dwordx2 v3, v[72:73], s[6:7]
	global_store_dwordx2 v3, v[74:75], s[6:7] offset:512
	global_store_dwordx2 v3, v[76:77], s[6:7] offset:1024
	global_store_dwordx2 v3, v[78:79], s[6:7] offset:1536
	s_add_u32 s6, s6, 0x400000
	s_addc_u32 s7, s7, 0
	global_load_dwordx4 v[40:43], v2, s[4:5]
	global_load_dwordx4 v[44:47], v2, s[4:5] offset:1024
	global_load_dwordx4 v[48:51], v2, s[4:5] offset:2048
	global_load_dwordx4 v[52:55], v2, s[4:5] offset:3072
	s_add_u32 s4, s4, 0x800000
	s_addc_u32 s5, s5, 0
	s_waitcnt vmcnt(8)
	v_pk_fma_f32 v[56:57], v[56:57], v[24:25], v[8:9]
	v_pk_fma_f32 v[58:59], v[58:59], v[26:27], v[10:11]
	v_pk_fma_f32 v[60:61], v[60:61], v[28:29], v[12:13]
	v_pk_fma_f32 v[62:63], v[62:63], v[30:31], v[14:15]
	v_pk_fma_f32 v[64:65], v[64:65], v[32:33], v[16:17]
	v_pk_fma_f32 v[66:67], v[66:67], v[34:35], v[18:19]
	v_pk_fma_f32 v[68:69], v[68:69], v[36:37], v[20:21]
	v_pk_fma_f32 v[70:71], v[70:71], v[38:39], v[22:23]
	v_cvt_pk_bf16_f32 v80, v56, v57
	v_cvt_pk_bf16_f32 v81, v58, v59
	v_cvt_pk_bf16_f32 v82, v60, v61
	v_cvt_pk_bf16_f32 v83, v62, v63
	v_cvt_pk_bf16_f32 v84, v64, v65
	v_cvt_pk_bf16_f32 v85, v66, v67
	v_cvt_pk_bf16_f32 v86, v68, v69
	v_cvt_pk_bf16_f32 v87, v70, v71
	global_store_dwordx2 v3, v[80:81], s[6:7]
	global_store_dwordx2 v3, v[82:83], s[6:7] offset:512
	global_store_dwordx2 v3, v[84:85], s[6:7] offset:1024
	global_store_dwordx2 v3, v[86:87], s[6:7] offset:1536
	s_add_u32 s6, s6, 0x400000
	s_addc_u32 s7, s7, 0
	global_load_dwordx4 v[56:59], v2, s[4:5]
	global_load_dwordx4 v[60:63], v2, s[4:5] offset:1024
	global_load_dwordx4 v[64:67], v2, s[4:5] offset:2048
	global_load_dwordx4 v[68:71], v2, s[4:5] offset:3072
	s_add_u32 s4, s4, 0x800000
	s_addc_u32 s5, s5, 0
	s_waitcnt vmcnt(8)
	v_pk_fma_f32 v[40:41], v[40:41], v[24:25], v[8:9]
	v_pk_fma_f32 v[42:43], v[42:43], v[26:27], v[10:11]
	v_pk_fma_f32 v[44:45], v[44:45], v[28:29], v[12:13]
	v_pk_fma_f32 v[46:47], v[46:47], v[30:31], v[14:15]
	v_pk_fma_f32 v[48:49], v[48:49], v[32:33], v[16:17]
	v_pk_fma_f32 v[50:51], v[50:51], v[34:35], v[18:19]
	v_pk_fma_f32 v[52:53], v[52:53], v[36:37], v[20:21]
	v_pk_fma_f32 v[54:55], v[54:55], v[38:39], v[22:23]
	v_cvt_pk_bf16_f32 v72, v40, v41
	v_cvt_pk_bf16_f32 v73, v42, v43
	v_cvt_pk_bf16_f32 v74, v44, v45
	v_cvt_pk_bf16_f32 v75, v46, v47
	v_cvt_pk_bf16_f32 v76, v48, v49
	v_cvt_pk_bf16_f32 v77, v50, v51
	v_cvt_pk_bf16_f32 v78, v52, v53
	v_cvt_pk_bf16_f32 v79, v54, v55
	global_store_dwordx2 v3, v[72:73], s[6:7]
	global_store_dwordx2 v3, v[74:75], s[6:7] offset:512
	global_store_dwordx2 v3, v[76:77], s[6:7] offset:1024
	global_store_dwordx2 v3, v[78:79], s[6:7] offset:1536
	s_add_u32 s6, s6, 0x400000
	s_addc_u32 s7, s7, 0
	global_load_dwordx4 v[40:43], v2, s[4:5]
	global_load_dwordx4 v[44:47], v2, s[4:5] offset:1024
	global_load_dwordx4 v[48:51], v2, s[4:5] offset:2048
	global_load_dwordx4 v[52:55], v2, s[4:5] offset:3072
	s_add_u32 s4, s4, 0x800000
	s_addc_u32 s5, s5, 0
	s_waitcnt vmcnt(8)
	v_pk_fma_f32 v[56:57], v[56:57], v[24:25], v[8:9]
	v_pk_fma_f32 v[58:59], v[58:59], v[26:27], v[10:11]
	v_pk_fma_f32 v[60:61], v[60:61], v[28:29], v[12:13]
	v_pk_fma_f32 v[62:63], v[62:63], v[30:31], v[14:15]
	v_pk_fma_f32 v[64:65], v[64:65], v[32:33], v[16:17]
	v_pk_fma_f32 v[66:67], v[66:67], v[34:35], v[18:19]
	v_pk_fma_f32 v[68:69], v[68:69], v[36:37], v[20:21]
	v_pk_fma_f32 v[70:71], v[70:71], v[38:39], v[22:23]
	v_cvt_pk_bf16_f32 v80, v56, v57
	v_cvt_pk_bf16_f32 v81, v58, v59
	v_cvt_pk_bf16_f32 v82, v60, v61
	v_cvt_pk_bf16_f32 v83, v62, v63
	v_cvt_pk_bf16_f32 v84, v64, v65
	v_cvt_pk_bf16_f32 v85, v66, v67
	v_cvt_pk_bf16_f32 v86, v68, v69
	v_cvt_pk_bf16_f32 v87, v70, v71
	global_store_dwordx2 v3, v[80:81], s[6:7]
	global_store_dwordx2 v3, v[82:83], s[6:7] offset:512
	global_store_dwordx2 v3, v[84:85], s[6:7] offset:1024
	global_store_dwordx2 v3, v[86:87], s[6:7] offset:1536
	s_add_u32 s6, s6, 0x400000
	s_addc_u32 s7, s7, 0
	global_load_dwordx4 v[56:59], v2, s[4:5]
	global_load_dwordx4 v[60:63], v2, s[4:5] offset:1024
	global_load_dwordx4 v[64:67], v2, s[4:5] offset:2048
	global_load_dwordx4 v[68:71], v2, s[4:5] offset:3072
	s_add_u32 s4, s4, 0x800000
	s_addc_u32 s5, s5, 0
	s_waitcnt vmcnt(8)
	v_pk_fma_f32 v[40:41], v[40:41], v[24:25], v[8:9]
	v_pk_fma_f32 v[42:43], v[42:43], v[26:27], v[10:11]
	v_pk_fma_f32 v[44:45], v[44:45], v[28:29], v[12:13]
	v_pk_fma_f32 v[46:47], v[46:47], v[30:31], v[14:15]
	v_pk_fma_f32 v[48:49], v[48:49], v[32:33], v[16:17]
	v_pk_fma_f32 v[50:51], v[50:51], v[34:35], v[18:19]
	v_pk_fma_f32 v[52:53], v[52:53], v[36:37], v[20:21]
	v_pk_fma_f32 v[54:55], v[54:55], v[38:39], v[22:23]
	v_cvt_pk_bf16_f32 v72, v40, v41
	v_cvt_pk_bf16_f32 v73, v42, v43
	v_cvt_pk_bf16_f32 v74, v44, v45
	v_cvt_pk_bf16_f32 v75, v46, v47
	v_cvt_pk_bf16_f32 v76, v48, v49
	v_cvt_pk_bf16_f32 v77, v50, v51
	v_cvt_pk_bf16_f32 v78, v52, v53
	v_cvt_pk_bf16_f32 v79, v54, v55
	global_store_dwordx2 v3, v[72:73], s[6:7]
	global_store_dwordx2 v3, v[74:75], s[6:7] offset:512
	global_store_dwordx2 v3, v[76:77], s[6:7] offset:1024
	global_store_dwordx2 v3, v[78:79], s[6:7] offset:1536
	s_add_u32 s6, s6, 0x400000
	s_addc_u32 s7, s7, 0
	global_load_dwordx4 v[40:43], v2, s[4:5]
	global_load_dwordx4 v[44:47], v2, s[4:5] offset:1024
	global_load_dwordx4 v[48:51], v2, s[4:5] offset:2048
	global_load_dwordx4 v[52:55], v2, s[4:5] offset:3072
	s_add_u32 s4, s4, 0x800000
	s_addc_u32 s5, s5, 0
	s_waitcnt vmcnt(8)
	v_pk_fma_f32 v[56:57], v[56:57], v[24:25], v[8:9]
	v_pk_fma_f32 v[58:59], v[58:59], v[26:27], v[10:11]
	v_pk_fma_f32 v[60:61], v[60:61], v[28:29], v[12:13]
	v_pk_fma_f32 v[62:63], v[62:63], v[30:31], v[14:15]
	v_pk_fma_f32 v[64:65], v[64:65], v[32:33], v[16:17]
	v_pk_fma_f32 v[66:67], v[66:67], v[34:35], v[18:19]
	v_pk_fma_f32 v[68:69], v[68:69], v[36:37], v[20:21]
	v_pk_fma_f32 v[70:71], v[70:71], v[38:39], v[22:23]
	v_cvt_pk_bf16_f32 v80, v56, v57
	v_cvt_pk_bf16_f32 v81, v58, v59
	v_cvt_pk_bf16_f32 v82, v60, v61
	v_cvt_pk_bf16_f32 v83, v62, v63
	v_cvt_pk_bf16_f32 v84, v64, v65
	v_cvt_pk_bf16_f32 v85, v66, v67
	v_cvt_pk_bf16_f32 v86, v68, v69
	v_cvt_pk_bf16_f32 v87, v70, v71
	global_store_dwordx2 v3, v[80:81], s[6:7]
	global_store_dwordx2 v3, v[82:83], s[6:7] offset:512
	global_store_dwordx2 v3, v[84:85], s[6:7] offset:1024
	global_store_dwordx2 v3, v[86:87], s[6:7] offset:1536
	s_add_u32 s6, s6, 0x400000
	s_addc_u32 s7, s7, 0
	global_load_dwordx4 v[56:59], v2, s[4:5]
	global_load_dwordx4 v[60:63], v2, s[4:5] offset:1024
	global_load_dwordx4 v[64:67], v2, s[4:5] offset:2048
	global_load_dwordx4 v[68:71], v2, s[4:5] offset:3072
	s_add_u32 s4, s4, 0x800000
	s_addc_u32 s5, s5, 0
	s_waitcnt vmcnt(8)
	v_pk_fma_f32 v[40:41], v[40:41], v[24:25], v[8:9]
	v_pk_fma_f32 v[42:43], v[42:43], v[26:27], v[10:11]
	v_pk_fma_f32 v[44:45], v[44:45], v[28:29], v[12:13]
	v_pk_fma_f32 v[46:47], v[46:47], v[30:31], v[14:15]
	v_pk_fma_f32 v[48:49], v[48:49], v[32:33], v[16:17]
	v_pk_fma_f32 v[50:51], v[50:51], v[34:35], v[18:19]
	v_pk_fma_f32 v[52:53], v[52:53], v[36:37], v[20:21]
	v_pk_fma_f32 v[54:55], v[54:55], v[38:39], v[22:23]
	v_cvt_pk_bf16_f32 v72, v40, v41
	v_cvt_pk_bf16_f32 v73, v42, v43
	v_cvt_pk_bf16_f32 v74, v44, v45
	v_cvt_pk_bf16_f32 v75, v46, v47
	v_cvt_pk_bf16_f32 v76, v48, v49
	v_cvt_pk_bf16_f32 v77, v50, v51
	v_cvt_pk_bf16_f32 v78, v52, v53
	v_cvt_pk_bf16_f32 v79, v54, v55
	global_store_dwordx2 v3, v[72:73], s[6:7]
	global_store_dwordx2 v3, v[74:75], s[6:7] offset:512
	global_store_dwordx2 v3, v[76:77], s[6:7] offset:1024
	global_store_dwordx2 v3, v[78:79], s[6:7] offset:1536
	s_add_u32 s6, s6, 0x400000
	s_addc_u32 s7, s7, 0
	s_waitcnt vmcnt(4)
	v_pk_fma_f32 v[56:57], v[56:57], v[24:25], v[8:9]
	v_pk_fma_f32 v[58:59], v[58:59], v[26:27], v[10:11]
	v_pk_fma_f32 v[60:61], v[60:61], v[28:29], v[12:13]
	v_pk_fma_f32 v[62:63], v[62:63], v[30:31], v[14:15]
	v_pk_fma_f32 v[64:65], v[64:65], v[32:33], v[16:17]
	v_pk_fma_f32 v[66:67], v[66:67], v[34:35], v[18:19]
	v_pk_fma_f32 v[68:69], v[68:69], v[36:37], v[20:21]
	v_pk_fma_f32 v[70:71], v[70:71], v[38:39], v[22:23]
	v_cvt_pk_bf16_f32 v80, v56, v57
	v_cvt_pk_bf16_f32 v81, v58, v59
	v_cvt_pk_bf16_f32 v82, v60, v61
	v_cvt_pk_bf16_f32 v83, v62, v63
	v_cvt_pk_bf16_f32 v84, v64, v65
	v_cvt_pk_bf16_f32 v85, v66, v67
	v_cvt_pk_bf16_f32 v86, v68, v69
	v_cvt_pk_bf16_f32 v87, v70, v71
	global_store_dwordx2 v3, v[80:81], s[6:7]
	global_store_dwordx2 v3, v[82:83], s[6:7] offset:512
	global_store_dwordx2 v3, v[84:85], s[6:7] offset:1024
	global_store_dwordx2 v3, v[86:87], s[6:7] offset:1536
	s_add_u32 s6, s6, 0x400000
	s_addc_u32 s7, s7, 0
	s_cmp_lt_u32 s33, 32
	s_cbranch_scc0 .Lp1_done
	s_add_u32 s4, s56, s10
	s_addc_u32 s5, s57, 0
	s_add_u32 s6, s54, s11
	s_addc_u32 s7, s55, 0
	s_add_u32 s6, s6, 0x2000000
	s_addc_u32 s7, s7, 0
	global_load_dwordx4 v[40:43], v2, s[4:5]
	global_load_dwordx4 v[44:47], v2, s[4:5] offset:1024
	global_load_dwordx4 v[48:51], v2, s[4:5] offset:2048
	global_load_dwordx4 v[52:55], v2, s[4:5] offset:3072
	ds_read_b128 v[8:11], v2 offset:8192
	ds_read_b128 v[12:15], v2 offset:9216
	ds_read_b128 v[16:19], v2 offset:10240
	ds_read_b128 v[20:23], v2 offset:11264
	ds_read_b128 v[24:27], v2 offset:12288
	ds_read_b128 v[28:31], v2 offset:13312
	ds_read_b128 v[32:35], v2 offset:14336
	ds_read_b128 v[36:39], v2 offset:15360
	s_waitcnt lgkmcnt(0)
	v_pk_add_f32 v[24:25], v[24:25], 1.0 op_sel_hi:[1,0]
	v_pk_add_f32 v[26:27], v[26:27], 1.0 op_sel_hi:[1,0]
	v_pk_add_f32 v[28:29], v[28:29], 1.0 op_sel_hi:[1,0]
	v_pk_add_f32 v[30:31], v[30:31], 1.0 op_sel_hi:[1,0]
	v_pk_add_f32 v[32:33], v[32:33], 1.0 op_sel_hi:[1,0]
	v_pk_add_f32 v[34:35], v[34:35], 1.0 op_sel_hi:[1,0]
	v_pk_add_f32 v[36:37], v[36:37], 1.0 op_sel_hi:[1,0]
	v_pk_add_f32 v[38:39], v[38:39], 1.0 op_sel_hi:[1,0]
	s_waitcnt vmcnt(0)
	v_pk_fma_f32 v[40:41], v[40:41], v[24:25], v[8:9]
	v_pk_fma_f32 v[42:43], v[42:43], v[26:27], v[10:11]
	v_pk_fma_f32 v[44:45], v[44:45], v[28:29], v[12:13]
	v_pk_fma_f32 v[46:47], v[46:47], v[30:31], v[14:15]
	v_pk_fma_f32 v[48:49], v[48:49], v[32:33], v[16:17]
	v_pk_fma_f32 v[50:51], v[50:51], v[34:35], v[18:19]
	v_pk_fma_f32 v[52:53], v[52:53], v[36:37], v[20:21]
	v_pk_fma_f32 v[54:55], v[54:55], v[38:39], v[22:23]
	v_cvt_pk_bf16_f32 v72, v40, v41
	v_cvt_pk_bf16_f32 v73, v42, v43
	v_cvt_pk_bf16_f32 v74, v44, v45
	v_cvt_pk_bf16_f32 v75, v46, v47
	v_cvt_pk_bf16_f32 v76, v48, v49
	v_cvt_pk_bf16_f32 v77, v50, v51
	v_cvt_pk_bf16_f32 v78, v52, v53
	v_cvt_pk_bf16_f32 v79, v54, v55
	global_store_dwordx2 v3, v[72:73], s[6:7]
	global_store_dwordx2 v3, v[74:75], s[6:7] offset:512
	global_store_dwordx2 v3, v[76:77], s[6:7] offset:1024
	global_store_dwordx2 v3, v[78:79], s[6:7] offset:1536
.Lp1_done:
.LBB0_131:
	s_or_b64 exec, exec, s[0:1]
	s_barrier
